# gdn_chunk conv staging: for 64-row chunks the second batch of 32 row loads is requested right behind the first (counted wait) and consumed from spare registers on the second trip, removing a second ex
# baseline (speedup 1.0000x reference)
; DI float bf2f(bf16_t b) { return __uint_as_float(((unsigned)b) << 16); }
; DI void gdn_chunk(CP c, int l, int item, float* sm) {
;     ...
;         const int part = tid >> 7, cc = tid & 127, col = part * 512 + h * 128 + cc;
;         const float* cw = c->in[I_GCW] + (size_t)l * 4 * 1536 + col; const float w0 = cw[0], w1 = cw[1536], w2 = cw[2 * 1536], w3 = cw[3 * 1536];
;         float x0 = 0.f, x1 = 0.f, x2 = 0.f;
;         if (samp) { const float* hs = c->in[I_SGC] + (size_t)(l * 32 + b) * 3 * 1536 + col; x0 = hs[0]; x1 = hs[1536]; x2 = hs[2 * 1536]; }
;         else if (n > 0) { const bf16_t* zz = Z1 + (size_t)(rbase - 3) * NZ1 + 1024 + col; x0 = bf2f(zz[0]); x1 = bf2f(zz[NZ1]); x2 = bf2f(zz[2 * NZ1]); }
;         float* dst = part == 0 ? Qs + cc : (part == 1 ? Ks + cc : R + cc); const int dstride = part == 2 ? 260 : 132;
;         const bf16_t* zr = Z1 + (size_t)rbase * NZ1 + 1024 + col;
; #pragma unroll 1
;         for (int i0 = 0; i0 < 64; i0 += 32) {
.LBB0_755:
	v_cmp_eq_u32_e32 vcc, 1, v8
	s_mul_i32 s0, s92, 0x1e00
	v_readlane_b32 s6, v254, 36
	v_cndmask_b32_e32 v0, v194, v190, vcc
	v_add_u32_e32 v0, 0, v0
	v_cmp_gt_u32_e32 vcc, s4, v80
	s_mul_hi_i32 s1, s92, 0x1e00
	v_readlane_b32 s7, v254, 37
	s_add_u32 s0, s6, s0
	v_cndmask_b32_e64 v0, v0, 0, vcc
	v_cmp_eq_u32_e32 vcc, 2, v8
	s_addc_u32 s1, s7, s1
	v_lshl_add_u32 v0, v9, 2, v0
	v_cndmask_b32_e32 v81, v202, v208, vcc
	v_lshl_add_u64 v[6:7], v[6:7], 1, s[0:1]
	s_waitcnt vmcnt(2)
	v_mov_b32_e32 v8, v3
	v_mov_b32_e32 v9, v2
	s_waitcnt vmcnt(1)
	v_mov_b32_e32 v10, v5
	s_waitcnt vmcnt(0)
	v_mov_b32_e32 v11, v4
	s_mov_b32 s0, 0
	s_mov_b64 s[26:27], -1
	s_mov_b32 s32, 0
	s_branch .LBB0_758

; DI float lo16(unsigned w) { return __uint_as_float(w << 16); }
; DI float silu(float x) { return x * __builtin_amdgcn_rcpf(1.f + fexp(-x)); }
; DI void gdn_chunk(CP c, int l, int item, float* sm) {
;     ...
;         for (int i0 = 0; i0 < 64; i0 += 32) {
;             unsigned xr[32];
; #pragma unroll
;             for (int k = 0; k < 32; ++k) xr[k] = (i0 + k < C) ? (unsigned)zr[(size_t)(i0 + k) * NZ1] : 0u;
; #pragma unroll
;             for (int k = 0; k < 32; ++k) { float y = 0.f;
;                 if (i0 + k < C) { const float x3 = lo16(xr[k]); y = silu(w0 * x0 + w1 * x1 + w2 * x2 + w3 * x3); x0 = x1; x1 = x2; x2 = x3; }
.LBB0_758:
	s_cmp_lg_u32 s0, 0
	s_cbranch_scc0 .Lgpf_norm
	s_cmp_lg_u32 s32, 0
	s_cbranch_scc0 .Lgpf_norm
	s_mov_b64 vcc, -1
	s_mov_b64 s[6:7], -1
	s_mov_b64 s[12:13], -1
	s_mov_b64 s[96:97], -1
	s_mov_b64 s[94:95], -1
	s_mov_b64 s[88:89], -1
	s_mov_b64 s[84:85], -1
	s_mov_b64 s[82:83], -1
	s_mov_b64 s[80:81], -1
	s_mov_b64 s[78:79], -1
	s_mov_b64 s[76:77], -1
	s_mov_b64 s[74:75], -1
	s_mov_b64 s[72:73], -1
	s_mov_b64 s[68:69], -1
	s_mov_b64 s[66:67], -1
	s_mov_b64 s[64:65], -1
	s_mov_b64 s[62:63], -1
	s_mov_b64 s[60:61], -1
	s_mov_b64 s[58:59], -1
	s_mov_b64 s[56:57], -1
	s_mov_b64 s[54:55], -1
	s_mov_b64 s[52:53], -1
	s_mov_b64 s[50:51], -1
	s_mov_b64 s[48:49], -1
	s_mov_b64 s[44:45], -1
	s_mov_b64 s[42:43], -1
	s_mov_b64 s[40:41], -1
	s_mov_b64 s[38:39], -1
	s_mov_b64 s[36:37], -1
	s_mov_b64 s[34:35], -1
	s_mov_b64 s[30:31], -1
	s_mov_b64 s[28:29], -1
	s_waitcnt vmcnt(0)
	v_lshlrev_b32_e32 v75, 16, v124
	v_lshlrev_b32_e32 v78, 16, v125
	v_lshlrev_b32_e32 v76, 16, v126
	v_lshlrev_b32_e32 v72, 16, v127
	v_lshlrev_b32_e32 v70, 16, v128
	v_lshlrev_b32_e32 v66, 16, v129
	v_lshlrev_b32_e32 v64, 16, v130
	v_lshlrev_b32_e32 v60, 16, v131
	v_lshlrev_b32_e32 v55, 16, v132
	v_lshlrev_b32_e32 v56, 16, v133
	v_lshlrev_b32_e32 v58, 16, v134
	v_lshlrev_b32_e32 v50, 16, v135
	v_lshlrev_b32_e32 v52, 16, v136
	v_lshlrev_b32_e32 v48, 16, v137
	v_lshlrev_b32_e32 v46, 16, v138
	v_lshlrev_b32_e32 v44, 16, v139
	v_lshlrev_b32_e32 v42, 16, v140
	v_lshlrev_b32_e32 v40, 16, v141
	v_lshlrev_b32_e32 v38, 16, v142
	v_lshlrev_b32_e32 v31, 16, v143
	v_lshlrev_b32_e32 v36, 16, v144
	v_lshlrev_b32_e32 v34, 16, v145
	v_lshlrev_b32_e32 v32, 16, v146
	v_lshlrev_b32_e32 v28, 16, v147
	v_lshlrev_b32_e32 v26, 16, v148
	v_lshlrev_b32_e32 v24, 16, v149
	v_lshlrev_b32_e32 v22, 16, v150
	v_lshlrev_b32_e32 v20, 16, v151
	v_lshlrev_b32_e32 v18, 16, v152
	v_lshlrev_b32_e32 v16, 16, v153
	v_lshlrev_b32_e32 v13, 16, v154
	v_lshlrev_b32_e32 v14, 16, v155
	s_branch .Lgpf_join

; DI void gdn_chunk(CP c, int l, int item, float* sm) {
;     ...
;         for (int i0 = 0; i0 < 64; i0 += 32) {
;             unsigned xr[32];
; #pragma unroll
;             for (int k = 0; k < 32; ++k) xr[k] = (i0 + k < C) ? (unsigned)zr[(size_t)(i0 + k) * NZ1] : 0u;
.LBB0_822:
	s_cmp_eq_u32 s93, 64
	s_cbranch_scc0 .Lgpf_w0
	s_cmp_lg_u32 s0, 0
	s_cbranch_scc1 .Lgpf_w0
	s_mov_b32 s32, 1
	s_mov_b32 s99, 0
	s_mov_b32 s98, 0x1e000
	v_lshl_add_u64 v[84:85], s[98:99], 1, v[6:7]
	global_load_ushort v124, v[84:85], off offset:2048
	s_mov_b32 s98, 0x1ef00
	v_lshl_add_u64 v[84:85], s[98:99], 1, v[6:7]
	global_load_ushort v125, v[84:85], off offset:2048
	s_mov_b32 s98, 0x1fe00
	v_lshl_add_u64 v[84:85], s[98:99], 1, v[6:7]
	global_load_ushort v126, v[84:85], off offset:2048
	s_mov_b32 s98, 0x20d00
	v_lshl_add_u64 v[84:85], s[98:99], 1, v[6:7]
	global_load_ushort v127, v[84:85], off offset:2048
	s_mov_b32 s98, 0x21c00
	v_lshl_add_u64 v[84:85], s[98:99], 1, v[6:7]
	global_load_ushort v128, v[84:85], off offset:2048
	s_mov_b32 s98, 0x22b00
	v_lshl_add_u64 v[84:85], s[98:99], 1, v[6:7]
	global_load_ushort v129, v[84:85], off offset:2048
	s_mov_b32 s98, 0x23a00
	v_lshl_add_u64 v[84:85], s[98:99], 1, v[6:7]
	global_load_ushort v130, v[84:85], off offset:2048
	s_mov_b32 s98, 0x24900
	v_lshl_add_u64 v[84:85], s[98:99], 1, v[6:7]
	global_load_ushort v131, v[84:85], off offset:2048
	s_mov_b32 s98, 0x25800
	v_lshl_add_u64 v[84:85], s[98:99], 1, v[6:7]
	global_load_ushort v132, v[84:85], off offset:2048
	s_mov_b32 s98, 0x26700
	v_lshl_add_u64 v[84:85], s[98:99], 1, v[6:7]
	global_load_ushort v133, v[84:85], off offset:2048
	s_mov_b32 s98, 0x27600
	v_lshl_add_u64 v[84:85], s[98:99], 1, v[6:7]
	global_load_ushort v134, v[84:85], off offset:2048
	s_mov_b32 s98, 0x28500
	v_lshl_add_u64 v[84:85], s[98:99], 1, v[6:7]
	global_load_ushort v135, v[84:85], off offset:2048
	s_mov_b32 s98, 0x29400
	v_lshl_add_u64 v[84:85], s[98:99], 1, v[6:7]
	global_load_ushort v136, v[84:85], off offset:2048
	s_mov_b32 s98, 0x2a300
	v_lshl_add_u64 v[84:85], s[98:99], 1, v[6:7]
	global_load_ushort v137, v[84:85], off offset:2048
	s_mov_b32 s98, 0x2b200
	v_lshl_add_u64 v[84:85], s[98:99], 1, v[6:7]
	global_load_ushort v138, v[84:85], off offset:2048
	s_mov_b32 s98, 0x2c100
	v_lshl_add_u64 v[84:85], s[98:99], 1, v[6:7]
	global_load_ushort v139, v[84:85], off offset:2048
	s_mov_b32 s98, 0x2d000
	v_lshl_add_u64 v[84:85], s[98:99], 1, v[6:7]
	global_load_ushort v140, v[84:85], off offset:2048
	s_mov_b32 s98, 0x2df00
	v_lshl_add_u64 v[84:85], s[98:99], 1, v[6:7]
	global_load_ushort v141, v[84:85], off offset:2048
	s_mov_b32 s98, 0x2ee00
	v_lshl_add_u64 v[84:85], s[98:99], 1, v[6:7]
	global_load_ushort v142, v[84:85], off offset:2048
	s_mov_b32 s98, 0x2fd00
	v_lshl_add_u64 v[84:85], s[98:99], 1, v[6:7]
	global_load_ushort v143, v[84:85], off offset:2048
	s_mov_b32 s98, 0x30c00
	v_lshl_add_u64 v[84:85], s[98:99], 1, v[6:7]
	global_load_ushort v144, v[84:85], off offset:2048
	s_mov_b32 s98, 0x31b00
	v_lshl_add_u64 v[84:85], s[98:99], 1, v[6:7]
	global_load_ushort v145, v[84:85], off offset:2048
	s_mov_b32 s98, 0x32a00
	v_lshl_add_u64 v[84:85], s[98:99], 1, v[6:7]
	global_load_ushort v146, v[84:85], off offset:2048
	s_mov_b32 s98, 0x33900
	v_lshl_add_u64 v[84:85], s[98:99], 1, v[6:7]
	global_load_ushort v147, v[84:85], off offset:2048
	s_mov_b32 s98, 0x34800
	v_lshl_add_u64 v[84:85], s[98:99], 1, v[6:7]
	global_load_ushort v148, v[84:85], off offset:2048
	s_mov_b32 s98, 0x35700
	v_lshl_add_u64 v[84:85], s[98:99], 1, v[6:7]
	global_load_ushort v149, v[84:85], off offset:2048
	s_mov_b32 s98, 0x36600
	v_lshl_add_u64 v[84:85], s[98:99], 1, v[6:7]
	global_load_ushort v150, v[84:85], off offset:2048
	s_mov_b32 s98, 0x37500
	v_lshl_add_u64 v[84:85], s[98:99], 1, v[6:7]
	global_load_ushort v151, v[84:85], off offset:2048
	s_mov_b32 s98, 0x38400
	v_lshl_add_u64 v[84:85], s[98:99], 1, v[6:7]
	global_load_ushort v152, v[84:85], off offset:2048
	s_mov_b32 s98, 0x39300
	v_lshl_add_u64 v[84:85], s[98:99], 1, v[6:7]
	global_load_ushort v153, v[84:85], off offset:2048
	s_mov_b32 s98, 0x3a200
	v_lshl_add_u64 v[84:85], s[98:99], 1, v[6:7]
	global_load_ushort v154, v[84:85], off offset:2048
	s_mov_b32 s98, 0x3b100
	v_lshl_add_u64 v[84:85], s[98:99], 1, v[6:7]
	global_load_ushort v155, v[84:85], off offset:2048
	s_waitcnt vmcnt(32)
	s_branch .Lgpf_w1

; DI float lo16(unsigned w) { return __uint_as_float(w << 16); }
; DI float silu(float x) { return x * __builtin_amdgcn_rcpf(1.f + fexp(-x)); }
; DI void gdn_chunk(CP c, int l, int item, float* sm) {
;     ...
;             for (int k = 0; k < 32; ++k) xr[k] = (i0 + k < C) ? (unsigned)zr[(size_t)(i0 + k) * NZ1] : 0u;
; #pragma unroll
;             for (int k = 0; k < 32; ++k) { float y = 0.f;
;                 if (i0 + k < C) { const float x3 = lo16(xr[k]); y = silu(w0 * x0 + w1 * x1 + w2 * x2 + w3 * x3); x0 = x1; x1 = x2; x2 = x3; }
.Lgpf_w1:
	v_lshlrev_b32_e32 v75, 16, v75
	v_lshlrev_b32_e32 v78, 16, v78
	v_lshlrev_b32_e32 v76, 16, v76
	v_lshlrev_b32_e32 v72, 16, v72
	v_lshlrev_b32_e32 v70, 16, v70
	v_lshlrev_b32_e32 v66, 16, v66
	v_lshlrev_b32_e32 v64, 16, v64
	v_lshlrev_b32_e32 v60, 16, v60
	v_lshlrev_b32_e32 v55, 16, v55
	v_lshlrev_b32_e32 v56, 16, v56
	v_lshlrev_b32_e32 v58, 16, v58
	v_lshlrev_b32_e32 v50, 16, v50
	v_lshlrev_b32_e32 v52, 16, v52
	v_lshlrev_b32_e32 v48, 16, v48
	v_lshlrev_b32_e32 v46, 16, v46
	v_lshlrev_b32_e32 v44, 16, v44
	v_lshlrev_b32_e32 v42, 16, v42
	v_lshlrev_b32_e32 v40, 16, v40
	v_lshlrev_b32_e32 v38, 16, v38
	v_lshlrev_b32_e32 v31, 16, v31
	v_lshlrev_b32_e32 v36, 16, v36
	v_lshlrev_b32_e32 v34, 16, v34
	v_lshlrev_b32_e32 v32, 16, v32
	v_lshlrev_b32_e32 v28, 16, v28
	v_lshlrev_b32_e32 v26, 16, v26
	v_lshlrev_b32_e32 v24, 16, v24
	v_lshlrev_b32_e32 v22, 16, v22
	v_lshlrev_b32_e32 v20, 16, v20
	v_lshlrev_b32_e32 v18, 16, v18
	v_lshlrev_b32_e32 v16, 16, v16
	v_lshlrev_b32_e32 v13, 16, v13
	v_lshlrev_b32_e32 v14, 16, v14
